# grid barrier: last XCD leader releases all XCC generation words itself (one hop less), other leaders no longer re-release; on top of previous
# speedup vs baseline: 1.0037x; 1.0012x over previous
; __device__ __forceinline__ unsigned xb_ld(unsigned* p)              { return __hip_atomic_load(p, __ATOMIC_RELAXED, __HIP_MEMORY_SCOPE_AGENT); }
; __device__ __forceinline__ unsigned xb_add(unsigned* p, unsigned v) { return __hip_atomic_fetch_add(p, v, __ATOMIC_RELAXED, __HIP_MEMORY_SCOPE_AGENT); }
; #define XB_SPIN(cond, bar) do { unsigned _sp = 0; while (cond) { __builtin_amdgcn_s_sleep(1); \
;     if ((++_sp & 255u) == 0u) { if (xb_ld(&(bar)[XB_TMO])) break; if (_sp > XB_SPIN_CAP) { atomicAdd(&(bar)[XB_TMO], 1u); break; } } } } while (0)
; __device__ __forceinline__ void xcd_barrier_t0(const XcdBarrier& b, const bool wb = true) {
;     ...
;             const unsigned og = xb_add(&bar[XB_TOP], 1u);
;             const unsigned tg = og / nx;
;             if (og + 1u == (tg + 1u) * nx) xb_add(&bar[XB_TOPGEN], 1u);
;             else XB_SPIN(xb_ld(&bar[XB_TOPGEN]) == tg, bar);
;             __builtin_amdgcn_fence(__ATOMIC_ACQUIRE, "workgroup");
;             xb_add(&bar[XB_XGEN(b.x)], 1u);
.LBB0_596:
	s_or_b64 exec, exec, s[16:17]
	s_waitcnt vmcnt(0)
	v_readfirstlane_b32 s0, v3
	s_waitcnt lgkmcnt(0)
	v_sub_u32_e32 v4, 0, v2
	s_mov_b64 s[16:17], -1
	v_add_u32_e32 v3, s0, v0
	v_cvt_f32_u32_e32 v0, v2
	v_readlane_b32 s0, v251, 37
	v_readlane_b32 s1, v251, 38
	v_rcp_iflag_f32_e32 v0, v0
	s_nop 0
	v_mul_f32_e32 v0, 0x4f7ffffe, v0
	v_cvt_u32_f32_e32 v0, v0
	v_mul_lo_u32 v4, v4, v0
	v_mul_hi_u32 v4, v0, v4
	v_add_u32_e32 v0, v0, v4
	v_mul_hi_u32 v0, v3, v0
	v_mul_lo_u32 v4, v0, v2
	v_sub_u32_e32 v4, v3, v4
	v_cmp_ge_u32_e32 vcc, v4, v2
	v_add_u32_e32 v5, 1, v0
	v_add_u32_e32 v3, 1, v3
	v_cndmask_b32_e32 v0, v0, v5, vcc
	v_sub_u32_e32 v5, v4, v2
	v_cndmask_b32_e32 v4, v4, v5, vcc
	v_cmp_ge_u32_e32 vcc, v4, v2
	v_add_u32_e32 v4, 1, v0
	s_nop 0
	v_cndmask_b32_e32 v0, v0, v4, vcc
	v_mul_lo_u32 v4, v2, v0
	v_add_u32_e32 v2, v4, v2
	v_cmp_ne_u32_e32 vcc, v3, v2
	v_mov_b64_e32 v[2:3], s[0:1]
	s_cbranch_vccnz .Lxb_fo_7
	s_add_u32 s0, s0, 0xffffef00
	s_addc_u32 s1, s1, -1
	global_atomic_add v1, v215, s[0:1]
	s_add_u32 s0, s0, 0x100
	s_addc_u32 s1, s1, 0
	global_atomic_add v1, v215, s[0:1]
	s_add_u32 s0, s0, 0x100
	s_addc_u32 s1, s1, 0
	global_atomic_add v1, v215, s[0:1]
	s_add_u32 s0, s0, 0x100
	s_addc_u32 s1, s1, 0
	global_atomic_add v1, v215, s[0:1]
	s_add_u32 s0, s0, 0x100
	s_addc_u32 s1, s1, 0
	global_atomic_add v1, v215, s[0:1]
	s_add_u32 s0, s0, 0x100
	s_addc_u32 s1, s1, 0
	global_atomic_add v1, v215, s[0:1]
	s_add_u32 s0, s0, 0x100
	s_addc_u32 s1, s1, 0
	global_atomic_add v1, v215, s[0:1]
	s_add_u32 s0, s0, 0x100
	s_addc_u32 s1, s1, 0
	global_atomic_add v1, v215, s[0:1]
	s_add_u32 s0, s0, 0x100
	s_addc_u32 s1, s1, 0
	global_atomic_add v1, v215, s[0:1]
	s_add_u32 s0, s0, 0x100
	s_addc_u32 s1, s1, 0
	global_atomic_add v1, v215, s[0:1]
	s_add_u32 s0, s0, 0x100
	s_addc_u32 s1, s1, 0
	global_atomic_add v1, v215, s[0:1]
	s_add_u32 s0, s0, 0x100
	s_addc_u32 s1, s1, 0
	global_atomic_add v1, v215, s[0:1]
	s_add_u32 s0, s0, 0x100
	s_addc_u32 s1, s1, 0
	global_atomic_add v1, v215, s[0:1]
	s_add_u32 s0, s0, 0x100
	s_addc_u32 s1, s1, 0
	global_atomic_add v1, v215, s[0:1]
	s_add_u32 s0, s0, 0x100
	s_addc_u32 s1, s1, 0
	global_atomic_add v1, v215, s[0:1]
	s_add_u32 s0, s0, 0x100
	s_addc_u32 s1, s1, 0
	global_atomic_add v1, v215, s[0:1]
.Lxb_fo_7:
	s_and_saveexec_b64 s[14:15], vcc
	s_cbranch_execz .LBB0_608
	v_readlane_b32 s0, v251, 37
	v_readlane_b32 s1, v251, 38
	s_mov_b64 s[18:19], 0
	s_nop 3
	global_load_dword v2, v1, s[0:1] sc1
	s_waitcnt vmcnt(0)
	v_cmp_eq_u32_e32 vcc, v2, v0
	s_and_saveexec_b64 s[16:17], vcc
	s_cbranch_execz .LBB0_607
	s_mov_b32 s0, 1
	s_branch .LBB0_600

; __device__ __forceinline__ unsigned xb_add(unsigned* p, unsigned v) { return __hip_atomic_fetch_add(p, v, __ATOMIC_RELAXED, __HIP_MEMORY_SCOPE_AGENT); }
; __device__ __forceinline__ void xcd_barrier_t0(const XcdBarrier& b, const bool wb = true) {
;     ...
;             __builtin_amdgcn_fence(__ATOMIC_ACQUIRE, "workgroup");
;             xb_add(&bar[XB_XGEN(b.x)], 1u);
;             asm volatile("s_waitcnt vmcnt(0)" ::: "memory");
.LBB0_610:
	s_or_b64 exec, exec, s[14:15]
	s_mov_b64 s[14:15], exec
	v_mbcnt_lo_u32_b32 v0, s14, 0
	v_mbcnt_hi_u32_b32 v0, s15, v0
	v_cmp_eq_u32_e32 vcc, 0, v0
	s_and_saveexec_b64 s[16:17], vcc
	s_cbranch_execz .LBB0_612
	s_bcnt1_i32_b64 s0, s[14:15]
	v_mov_b32_e32 v0, s0
	v_mov_b32_e32 v2, 0x2000
.LBB0_612:
	s_or_b64 exec, exec, s[16:17]
	s_waitcnt vmcnt(0)

; __device__ __forceinline__ unsigned xb_ld(unsigned* p)              { return __hip_atomic_load(p, __ATOMIC_RELAXED, __HIP_MEMORY_SCOPE_AGENT); }
; __device__ __forceinline__ unsigned xb_add(unsigned* p, unsigned v) { return __hip_atomic_fetch_add(p, v, __ATOMIC_RELAXED, __HIP_MEMORY_SCOPE_AGENT); }
; #define XB_SPIN(cond, bar) do { unsigned _sp = 0; while (cond) { __builtin_amdgcn_s_sleep(1); \
;     if ((++_sp & 255u) == 0u) { if (xb_ld(&(bar)[XB_TMO])) break; if (_sp > XB_SPIN_CAP) { atomicAdd(&(bar)[XB_TMO], 1u); break; } } } } while (0)
; __device__ __forceinline__ void xcd_barrier_t0(const XcdBarrier& b, const bool wb = true) {
;     ...
;             const unsigned og = xb_add(&bar[XB_TOP], 1u);
;             const unsigned tg = og / nx;
;             if (og + 1u == (tg + 1u) * nx) xb_add(&bar[XB_TOPGEN], 1u);
;             else XB_SPIN(xb_ld(&bar[XB_TOPGEN]) == tg, bar);
;             __builtin_amdgcn_fence(__ATOMIC_ACQUIRE, "workgroup");
;             xb_add(&bar[XB_XGEN(b.x)], 1u);
.LBB0_650:
	s_or_b64 exec, exec, s[16:17]
	s_waitcnt vmcnt(0)
	v_readfirstlane_b32 s0, v3
	v_sub_u32_e32 v4, 0, v2
	s_mov_b64 s[16:17], -1
	v_add_u32_e32 v3, s0, v0
	v_cvt_f32_u32_e32 v0, v2
	v_readlane_b32 s0, v251, 37
	v_readlane_b32 s1, v251, 38
	v_rcp_iflag_f32_e32 v0, v0
	s_nop 0
	v_mul_f32_e32 v0, 0x4f7ffffe, v0
	v_cvt_u32_f32_e32 v0, v0
	v_mul_lo_u32 v4, v4, v0
	v_mul_hi_u32 v4, v0, v4
	v_add_u32_e32 v0, v0, v4
	v_mul_hi_u32 v0, v3, v0
	v_mul_lo_u32 v4, v0, v2
	v_sub_u32_e32 v4, v3, v4
	v_cmp_ge_u32_e32 vcc, v4, v2
	v_add_u32_e32 v5, 1, v0
	v_add_u32_e32 v3, 1, v3
	v_cndmask_b32_e32 v0, v0, v5, vcc
	v_sub_u32_e32 v5, v4, v2
	v_cndmask_b32_e32 v4, v4, v5, vcc
	v_cmp_ge_u32_e32 vcc, v4, v2
	v_add_u32_e32 v4, 1, v0
	s_nop 0
	v_cndmask_b32_e32 v0, v0, v4, vcc
	v_mul_lo_u32 v4, v2, v0
	v_add_u32_e32 v2, v4, v2
	v_cmp_ne_u32_e32 vcc, v3, v2
	v_mov_b64_e32 v[2:3], s[0:1]
	s_cbranch_vccnz .Lxb_fo_6
	s_add_u32 s0, s0, 0xffffef00
	s_addc_u32 s1, s1, -1
	global_atomic_add v1, v215, s[0:1]
	s_add_u32 s0, s0, 0x100
	s_addc_u32 s1, s1, 0
	global_atomic_add v1, v215, s[0:1]
	s_add_u32 s0, s0, 0x100
	s_addc_u32 s1, s1, 0
	global_atomic_add v1, v215, s[0:1]
	s_add_u32 s0, s0, 0x100
	s_addc_u32 s1, s1, 0
	global_atomic_add v1, v215, s[0:1]
	s_add_u32 s0, s0, 0x100
	s_addc_u32 s1, s1, 0
	global_atomic_add v1, v215, s[0:1]
	s_add_u32 s0, s0, 0x100
	s_addc_u32 s1, s1, 0
	global_atomic_add v1, v215, s[0:1]
	s_add_u32 s0, s0, 0x100
	s_addc_u32 s1, s1, 0
	global_atomic_add v1, v215, s[0:1]
	s_add_u32 s0, s0, 0x100
	s_addc_u32 s1, s1, 0
	global_atomic_add v1, v215, s[0:1]
	s_add_u32 s0, s0, 0x100
	s_addc_u32 s1, s1, 0
	global_atomic_add v1, v215, s[0:1]
	s_add_u32 s0, s0, 0x100
	s_addc_u32 s1, s1, 0
	global_atomic_add v1, v215, s[0:1]
	s_add_u32 s0, s0, 0x100
	s_addc_u32 s1, s1, 0
	global_atomic_add v1, v215, s[0:1]
	s_add_u32 s0, s0, 0x100
	s_addc_u32 s1, s1, 0
	global_atomic_add v1, v215, s[0:1]
	s_add_u32 s0, s0, 0x100
	s_addc_u32 s1, s1, 0
	global_atomic_add v1, v215, s[0:1]
	s_add_u32 s0, s0, 0x100
	s_addc_u32 s1, s1, 0
	global_atomic_add v1, v215, s[0:1]
	s_add_u32 s0, s0, 0x100
	s_addc_u32 s1, s1, 0
	global_atomic_add v1, v215, s[0:1]
	s_add_u32 s0, s0, 0x100
	s_addc_u32 s1, s1, 0
	global_atomic_add v1, v215, s[0:1]

; __device__ __forceinline__ unsigned xb_add(unsigned* p, unsigned v) { return __hip_atomic_fetch_add(p, v, __ATOMIC_RELAXED, __HIP_MEMORY_SCOPE_AGENT); }
; __device__ __forceinline__ void xcd_barrier_t0(const XcdBarrier& b, const bool wb = true) {
;     ...
;             __builtin_amdgcn_fence(__ATOMIC_ACQUIRE, "workgroup");
;             xb_add(&bar[XB_XGEN(b.x)], 1u);
;             asm volatile("s_waitcnt vmcnt(0)" ::: "memory");
.LBB0_664:
	s_or_b64 exec, exec, s[14:15]
	s_mov_b64 s[14:15], exec
	v_mbcnt_lo_u32_b32 v0, s14, 0
	v_mbcnt_hi_u32_b32 v0, s15, v0
	v_cmp_eq_u32_e32 vcc, 0, v0
	s_and_saveexec_b64 s[16:17], vcc
	s_cbranch_execz .LBB0_666
	s_bcnt1_i32_b64 s0, s[14:15]
	v_mov_b32_e32 v0, s0
	v_mov_b32_e32 v2, 0x2000
.LBB0_666:
	s_or_b64 exec, exec, s[16:17]
	s_waitcnt vmcnt(0)

; __device__ __forceinline__ unsigned xb_ld(unsigned* p)              { return __hip_atomic_load(p, __ATOMIC_RELAXED, __HIP_MEMORY_SCOPE_AGENT); }
; __device__ __forceinline__ unsigned xb_add(unsigned* p, unsigned v) { return __hip_atomic_fetch_add(p, v, __ATOMIC_RELAXED, __HIP_MEMORY_SCOPE_AGENT); }
; #define XB_SPIN(cond, bar) do { unsigned _sp = 0; while (cond) { __builtin_amdgcn_s_sleep(1); \
;     if ((++_sp & 255u) == 0u) { if (xb_ld(&(bar)[XB_TMO])) break; if (_sp > XB_SPIN_CAP) { atomicAdd(&(bar)[XB_TMO], 1u); break; } } } } while (0)
; __device__ __forceinline__ void xcd_barrier_t0(const XcdBarrier& b, const bool wb = true) {
;     ...
;             const unsigned og = xb_add(&bar[XB_TOP], 1u);
;             const unsigned tg = og / nx;
;             if (og + 1u == (tg + 1u) * nx) xb_add(&bar[XB_TOPGEN], 1u);
;             else XB_SPIN(xb_ld(&bar[XB_TOPGEN]) == tg, bar);
;             __builtin_amdgcn_fence(__ATOMIC_ACQUIRE, "workgroup");
;             xb_add(&bar[XB_XGEN(b.x)], 1u);
.LBB0_772:
	s_or_b64 exec, exec, s[18:19]
	s_waitcnt vmcnt(0)
	v_readfirstlane_b32 s0, v4
	v_cvt_f32_u32_e32 v4, v2
	v_sub_u32_e32 v5, 0, v2
	v_add_u32_e32 v3, s0, v3
	v_readlane_b32 s0, v251, 37
	v_rcp_iflag_f32_e32 v4, v4
	v_readlane_b32 s1, v251, 38
	s_mov_b64 s[18:19], -1
	v_mul_f32_e32 v4, 0x4f7ffffe, v4
	v_cvt_u32_f32_e32 v4, v4
	v_mul_lo_u32 v5, v5, v4
	v_mul_hi_u32 v5, v4, v5
	v_add_u32_e32 v4, v4, v5
	v_mul_hi_u32 v4, v3, v4
	v_mul_lo_u32 v5, v4, v2
	v_sub_u32_e32 v5, v3, v5
	v_cmp_ge_u32_e32 vcc, v5, v2
	v_add_u32_e32 v6, 1, v4
	v_add_u32_e32 v3, 1, v3
	v_cndmask_b32_e32 v4, v4, v6, vcc
	v_sub_u32_e32 v6, v5, v2
	v_cndmask_b32_e32 v5, v5, v6, vcc
	v_cmp_ge_u32_e32 vcc, v5, v2
	v_add_u32_e32 v5, 1, v4
	s_nop 0
	v_cndmask_b32_e32 v4, v4, v5, vcc
	v_mul_lo_u32 v5, v2, v4
	v_add_u32_e32 v2, v5, v2
	v_cmp_ne_u32_e32 vcc, v3, v2
	v_mov_b64_e32 v[2:3], s[0:1]
	s_cbranch_vccnz .Lxb_fo_5
	s_add_u32 s0, s0, 0xffffef00
	s_addc_u32 s1, s1, -1
	global_atomic_add v1, v215, s[0:1]
	s_add_u32 s0, s0, 0x100
	s_addc_u32 s1, s1, 0
	global_atomic_add v1, v215, s[0:1]
	s_add_u32 s0, s0, 0x100
	s_addc_u32 s1, s1, 0
	global_atomic_add v1, v215, s[0:1]
	s_add_u32 s0, s0, 0x100
	s_addc_u32 s1, s1, 0
	global_atomic_add v1, v215, s[0:1]
	s_add_u32 s0, s0, 0x100
	s_addc_u32 s1, s1, 0
	global_atomic_add v1, v215, s[0:1]
	s_add_u32 s0, s0, 0x100
	s_addc_u32 s1, s1, 0
	global_atomic_add v1, v215, s[0:1]
	s_add_u32 s0, s0, 0x100
	s_addc_u32 s1, s1, 0
	global_atomic_add v1, v215, s[0:1]
	s_add_u32 s0, s0, 0x100
	s_addc_u32 s1, s1, 0
	global_atomic_add v1, v215, s[0:1]
	s_add_u32 s0, s0, 0x100
	s_addc_u32 s1, s1, 0
	global_atomic_add v1, v215, s[0:1]
	s_add_u32 s0, s0, 0x100
	s_addc_u32 s1, s1, 0
	global_atomic_add v1, v215, s[0:1]
	s_add_u32 s0, s0, 0x100
	s_addc_u32 s1, s1, 0
	global_atomic_add v1, v215, s[0:1]
	s_add_u32 s0, s0, 0x100
	s_addc_u32 s1, s1, 0
	global_atomic_add v1, v215, s[0:1]
	s_add_u32 s0, s0, 0x100
	s_addc_u32 s1, s1, 0
	global_atomic_add v1, v215, s[0:1]
	s_add_u32 s0, s0, 0x100
	s_addc_u32 s1, s1, 0
	global_atomic_add v1, v215, s[0:1]
	s_add_u32 s0, s0, 0x100
	s_addc_u32 s1, s1, 0
	global_atomic_add v1, v215, s[0:1]
	s_add_u32 s0, s0, 0x100
	s_addc_u32 s1, s1, 0
	global_atomic_add v1, v215, s[0:1]
.Lxb_fo_5:
	s_and_saveexec_b64 s[16:17], vcc
	s_cbranch_execz .LBB0_784
	v_readlane_b32 s0, v251, 37
	v_readlane_b32 s1, v251, 38
	s_mov_b64 s[20:21], 0
	s_nop 3
	global_load_dword v2, v1, s[0:1] sc1
	s_waitcnt vmcnt(0)
	v_cmp_eq_u32_e32 vcc, v2, v4
	s_and_saveexec_b64 s[18:19], vcc
	s_cbranch_execz .LBB0_783
	s_mov_b32 s0, 1
	s_branch .LBB0_776

; __device__ __forceinline__ unsigned xb_add(unsigned* p, unsigned v) { return __hip_atomic_fetch_add(p, v, __ATOMIC_RELAXED, __HIP_MEMORY_SCOPE_AGENT); }
; __device__ __forceinline__ void xcd_barrier_t0(const XcdBarrier& b, const bool wb = true) {
;     ...
;             __builtin_amdgcn_fence(__ATOMIC_ACQUIRE, "workgroup");
;             xb_add(&bar[XB_XGEN(b.x)], 1u);
;             asm volatile("s_waitcnt vmcnt(0)" ::: "memory");
.LBB0_786:
	s_or_b64 exec, exec, s[16:17]
	s_mov_b64 s[16:17], exec
	v_mbcnt_lo_u32_b32 v2, s16, 0
	v_mbcnt_hi_u32_b32 v2, s17, v2
	v_cmp_eq_u32_e32 vcc, 0, v2
	s_and_saveexec_b64 s[18:19], vcc
	s_cbranch_execz .LBB0_788
	s_bcnt1_i32_b64 s0, s[16:17]
	v_mov_b32_e32 v2, s0
	v_mov_b32_e32 v3, 0x2000
.LBB0_788:
	s_or_b64 exec, exec, s[18:19]
	s_waitcnt vmcnt(0)

; __device__ __forceinline__ unsigned xb_add(unsigned* p, unsigned v) { return __hip_atomic_fetch_add(p, v, __ATOMIC_RELAXED, __HIP_MEMORY_SCOPE_AGENT); }
; __device__ __forceinline__ void xcd_barrier_t0(const XcdBarrier& b, const bool wb = true) {
;     ...
;             __builtin_amdgcn_fence(__ATOMIC_ACQUIRE, "workgroup");
;             xb_add(&bar[XB_XGEN(b.x)], 1u);
;             asm volatile("s_waitcnt vmcnt(0)" ::: "memory");
.LBB0_933:
	s_or_b64 exec, exec, s[16:17]
	s_mov_b64 s[16:17], exec
	v_mbcnt_lo_u32_b32 v2, s16, 0
	v_mbcnt_hi_u32_b32 v2, s17, v2
	v_cmp_eq_u32_e32 vcc, 0, v2
	s_and_saveexec_b64 s[18:19], vcc
	s_cbranch_execz .LBB0_935
	s_bcnt1_i32_b64 s0, s[16:17]
	v_mov_b32_e32 v2, s0
	v_mov_b32_e32 v3, 0x2000
.LBB0_935:
	s_or_b64 exec, exec, s[18:19]
	s_waitcnt vmcnt(0)

; __device__ __forceinline__ unsigned xb_add(unsigned* p, unsigned v) { return __hip_atomic_fetch_add(p, v, __ATOMIC_RELAXED, __HIP_MEMORY_SCOPE_AGENT); }
; __device__ __forceinline__ void xcd_barrier_t0(const XcdBarrier& b, const bool wb = true) {
;     ...
;             __builtin_amdgcn_fence(__ATOMIC_ACQUIRE, "workgroup");
;             xb_add(&bar[XB_XGEN(b.x)], 1u);
;             asm volatile("s_waitcnt vmcnt(0)" ::: "memory");
.LBB0_1058:
	s_or_b64 exec, exec, s[14:15]
	s_mov_b64 s[14:15], exec
	v_mbcnt_lo_u32_b32 v0, s14, 0
	v_mbcnt_hi_u32_b32 v0, s15, v0
	v_cmp_eq_u32_e32 vcc, 0, v0
	s_and_saveexec_b64 s[16:17], vcc
	s_cbranch_execz .LBB0_1060
	s_bcnt1_i32_b64 s0, s[14:15]
	v_mov_b32_e32 v0, s0
	v_mov_b32_e32 v2, 0x2000
.LBB0_1060:
	s_or_b64 exec, exec, s[16:17]
	s_waitcnt vmcnt(0)

; __device__ __forceinline__ unsigned xb_add(unsigned* p, unsigned v) { return __hip_atomic_fetch_add(p, v, __ATOMIC_RELAXED, __HIP_MEMORY_SCOPE_AGENT); }
; __device__ __forceinline__ void xcd_barrier_t0(const XcdBarrier& b, const bool wb = true) {
;     ...
;             __builtin_amdgcn_fence(__ATOMIC_ACQUIRE, "workgroup");
;             xb_add(&bar[XB_XGEN(b.x)], 1u);
;             asm volatile("s_waitcnt vmcnt(0)" ::: "memory");
.LBB0_1402:
	s_or_b64 exec, exec, s[14:15]
	s_mov_b64 s[14:15], exec
	v_mbcnt_lo_u32_b32 v0, s14, 0
	v_mbcnt_hi_u32_b32 v0, s15, v0
	v_cmp_eq_u32_e32 vcc, 0, v0
	s_and_saveexec_b64 s[16:17], vcc
	s_cbranch_execz .LBB0_1404
	s_bcnt1_i32_b64 s0, s[14:15]
	v_mov_b32_e32 v0, s0
	v_mov_b32_e32 v2, 0x2000
.LBB0_1404:
	s_or_b64 exec, exec, s[16:17]
	s_waitcnt vmcnt(0)

; __device__ __forceinline__ unsigned xb_add(unsigned* p, unsigned v) { return __hip_atomic_fetch_add(p, v, __ATOMIC_RELAXED, __HIP_MEMORY_SCOPE_AGENT); }
; __device__ __forceinline__ void xcd_barrier_t0(const XcdBarrier& b, const bool wb = true) {
;     ...
;             __builtin_amdgcn_fence(__ATOMIC_ACQUIRE, "workgroup");
;             xb_add(&bar[XB_XGEN(b.x)], 1u);
;             asm volatile("s_waitcnt vmcnt(0)" ::: "memory");
.LBB0_1760:
	s_or_b64 exec, exec, s[14:15]
	s_mov_b64 s[14:15], exec
	v_mbcnt_lo_u32_b32 v0, s14, 0
	v_mbcnt_hi_u32_b32 v0, s15, v0
	v_cmp_eq_u32_e32 vcc, 0, v0
	s_and_saveexec_b64 s[16:17], vcc
	s_cbranch_execz .LBB0_1762
	s_bcnt1_i32_b64 s0, s[14:15]
	v_mov_b32_e32 v0, s0
	v_mov_b32_e32 v2, 0x2000
.LBB0_1762:
	s_or_b64 exec, exec, s[16:17]
	s_waitcnt vmcnt(0)

; __device__ __forceinline__ unsigned xb_add(unsigned* p, unsigned v) { return __hip_atomic_fetch_add(p, v, __ATOMIC_RELAXED, __HIP_MEMORY_SCOPE_AGENT); }
; __device__ __forceinline__ void xcd_barrier_t0(const XcdBarrier& b, const bool wb = true) {
;     ...
;             __builtin_amdgcn_fence(__ATOMIC_ACQUIRE, "workgroup");
;             xb_add(&bar[XB_XGEN(b.x)], 1u);
;             asm volatile("s_waitcnt vmcnt(0)" ::: "memory");
.LBB0_1815:
	s_bcnt1_i32_b64 s0, s[14:15]
	v_mov_b32_e32 v0, s0
	v_mov_b32_e32 v2, 0x2000
	s_getpc_b64 s[98:99]
